# j=14 row loops rewritten (final_row_ss gains hoisted + loads batched; norm_row loads batched, DPP/permlane wave sum); plus all previous
# speedup vs baseline: 1.0511x; 1.0053x over previous
.LBB0_564:
	s_mov_b32 s0, -1
	s_nop 0
	v_mbcnt_lo_u32_b32 v0, s0, 0
	v_mbcnt_hi_u32_b32 v0, s0, v0
	v_readlane_b32 s0, v250, 25
	s_nop 1
	v_add_u32_e32 v0, s0, v0
	v_readlane_b32 s0, v250, 38
	v_readlane_b32 s1, v250, 39
	v_and_b32_e32 v10, 63, v0
	s_andn2_b64 vcc, exec, s[0:1]
	v_lshlrev_b32_e32 v2, 4, v10
	s_cbranch_vccnz .LBB0_567
	v_readlane_b32 s0, v254, 22
	s_add_u32 s0, s0, s86
	v_readlane_b32 s1, v254, 23
	v_mov_b32_e32 v3, v64
	v_readlane_b32 s36, v250, 1
	s_addc_u32 s1, s1, s87
	v_readlane_b32 s42, v250, 7
	v_readlane_b32 s43, v250, 8
	v_lshl_add_u64 v[4:5], s[0:1], 0, v[2:3]
	v_readlane_b32 s0, v254, 29
	s_waitcnt lgkmcnt(0)
	v_lshl_add_u64 v[0:1], s[42:43], 0, v[2:3]
	v_readlane_b32 s1, v254, 30
	v_readlane_b32 s2, v254, 55
	v_readlane_b32 s37, v250, 2
	v_readlane_b32 s38, v250, 3
	v_readlane_b32 s39, v250, 4
	v_readlane_b32 s40, v250, 5
	v_readlane_b32 s41, v250, 6
	v_readlane_b32 s3, v254, 56
	global_load_dwordx4 v[40:43], v[0:1], off
	global_load_dwordx4 v[44:47], v[0:1], off offset:1024
	global_load_dwordx4 v[48:51], v[0:1], off offset:2048
	global_load_dwordx4 v[52:55], v[0:1], off offset:3072
.LBB0_566:
	global_load_dwordx4 v[24:27], v64, s[0:1] offset:-48
	global_load_dwordx4 v[28:31], v64, s[0:1] offset:-32
	global_load_dwordx4 v[32:35], v64, s[0:1] offset:-16
	global_load_dwordx4 v[36:39], v64, s[0:1]
	global_load_dwordx4 v[6:9], v[4:5], off offset:-2048
	global_load_dwordx4 v[12:15], v[4:5], off offset:-1024
	global_load_dwordx4 v[16:19], v[4:5], off
	global_load_dwordx4 v[20:23], v[4:5], off offset:1024
	s_add_i32 s2, s2, s96
	s_add_u32 s0, s0, s74
	s_addc_u32 s1, s1, s75
	s_waitcnt vmcnt(4)
	v_add_f32_e32 v24, v24, v25
	v_add_f32_e32 v26, v26, v27
	v_add_f32_e32 v28, v28, v29
	v_add_f32_e32 v30, v30, v31
	v_add_f32_e32 v32, v32, v33
	v_add_f32_e32 v34, v34, v35
	v_add_f32_e32 v36, v36, v37
	v_add_f32_e32 v38, v38, v39
	v_add_f32_e32 v24, v24, v26
	v_add_f32_e32 v28, v28, v30
	v_add_f32_e32 v32, v32, v34
	v_add_f32_e32 v36, v36, v38
	v_add_f32_e32 v24, v24, v28
	v_add_f32_e32 v24, v24, v32
	v_add_f32_e32 v24, v24, v36
	v_fmamk_f32 v24, v24, 0x3a800000, v176
	v_rsq_f32_e32 v24, v24
	s_waitcnt vmcnt(0)
	v_pk_mul_f32 v[6:7], v[6:7], v[24:25] op_sel_hi:[1,0]
	v_pk_mul_f32 v[8:9], v[8:9], v[24:25] op_sel_hi:[1,0]
	v_pk_mul_f32 v[12:13], v[12:13], v[24:25] op_sel_hi:[1,0]
	v_pk_mul_f32 v[14:15], v[14:15], v[24:25] op_sel_hi:[1,0]
	v_pk_mul_f32 v[16:17], v[16:17], v[24:25] op_sel_hi:[1,0]
	v_pk_mul_f32 v[18:19], v[18:19], v[24:25] op_sel_hi:[1,0]
	v_pk_mul_f32 v[20:21], v[20:21], v[24:25] op_sel_hi:[1,0]
	v_pk_mul_f32 v[22:23], v[22:23], v[24:25] op_sel_hi:[1,0]
	v_pk_mul_f32 v[6:7], v[6:7], v[40:41]
	v_pk_mul_f32 v[8:9], v[8:9], v[42:43]
	v_pk_mul_f32 v[12:13], v[12:13], v[44:45]
	v_pk_mul_f32 v[14:15], v[14:15], v[46:47]
	v_pk_mul_f32 v[16:17], v[16:17], v[48:49]
	v_pk_mul_f32 v[18:19], v[18:19], v[50:51]
	v_pk_mul_f32 v[20:21], v[20:21], v[52:53]
	v_pk_mul_f32 v[22:23], v[22:23], v[54:55]
	global_store_dwordx4 v[4:5], v[6:9], off offset:-2048
	global_store_dwordx4 v[4:5], v[12:15], off offset:-1024
	global_store_dwordx4 v[4:5], v[16:19], off
	global_store_dwordx4 v[4:5], v[20:23], off offset:1024
	v_lshl_add_u64 v[4:5], v[4:5], 0, s[34:35]
	s_cmpk_gt_i32 s2, 0x3fff
	s_cbranch_scc0 .LBB0_566

.LBB0_569:
	global_load_dwordx4 v[10:13], v[2:3], off offset:-2048
	global_load_dwordx4 v[14:17], v[2:3], off offset:-1024
	global_load_dwordx4 v[18:21], v[2:3], off
	global_load_dwordx4 v[22:25], v[2:3], off offset:1024
	s_add_i32 s0, s0, s96
	v_lshl_add_u64 v[2:3], v[2:3], 0, s[34:35]
	s_waitcnt vmcnt(0)
	v_pk_mul_f32 v[26:27], v[10:11], v[10:11]
	v_pk_mul_f32 v[28:29], v[12:13], v[12:13]
	v_pk_fma_f32 v[26:27], v[14:15], v[14:15], v[26:27]
	v_pk_fma_f32 v[28:29], v[16:17], v[16:17], v[28:29]
	v_pk_fma_f32 v[26:27], v[18:19], v[18:19], v[26:27]
	v_pk_fma_f32 v[28:29], v[20:21], v[20:21], v[28:29]
	v_pk_fma_f32 v[26:27], v[22:23], v[22:23], v[26:27]
	v_pk_fma_f32 v[28:29], v[24:25], v[24:25], v[28:29]
	v_pk_add_f32 v[26:27], v[26:27], v[28:29]
	s_nop 0
	v_add_f32_e32 v26, v26, v27
	s_nop 1
	v_add_f32_dpp v26, v26, v26 row_ror:8 row_mask:0xf bank_mask:0xf
	s_nop 1
	v_add_f32_dpp v26, v26, v26 row_ror:4 row_mask:0xf bank_mask:0xf
	s_nop 1
	v_add_f32_dpp v26, v26, v26 row_ror:2 row_mask:0xf bank_mask:0xf
	s_nop 1
	v_add_f32_dpp v26, v26, v26 row_ror:1 row_mask:0xf bank_mask:0xf
	v_mov_b32_e32 v27, v26
	s_nop 1
	v_permlane16_swap_b32_e32 v27, v26
	v_add_f32_e32 v26, v27, v26
	v_mov_b32_e32 v27, v26
	s_nop 1
	v_permlane32_swap_b32_e32 v27, v26
	v_add_f32_e32 v26, v27, v26
	v_fmamk_f32 v26, v26, 0x3a800000, v176
	v_rsq_f32_e32 v26, v26
	s_nop 0
	v_pk_mul_f32 v[10:11], v[10:11], v[26:27] op_sel_hi:[1,0]
	v_pk_mul_f32 v[12:13], v[12:13], v[26:27] op_sel_hi:[1,0]
	v_pk_mul_f32 v[14:15], v[14:15], v[26:27] op_sel_hi:[1,0]
	v_pk_mul_f32 v[16:17], v[16:17], v[26:27] op_sel_hi:[1,0]
	v_pk_mul_f32 v[18:19], v[18:19], v[26:27] op_sel_hi:[1,0]
	v_pk_mul_f32 v[20:21], v[20:21], v[26:27] op_sel_hi:[1,0]
	v_pk_mul_f32 v[22:23], v[22:23], v[26:27] op_sel_hi:[1,0]
	v_pk_mul_f32 v[24:25], v[24:25], v[26:27] op_sel_hi:[1,0]
	v_cvt_pk_bf16_f32 v10, v10, v11
	v_cvt_pk_bf16_f32 v11, v12, v13
	global_store_dwordx2 v[0:1], v[10:11], off offset:-1536
	v_cvt_pk_bf16_f32 v14, v14, v15
	v_cvt_pk_bf16_f32 v15, v16, v17
	global_store_dwordx2 v[0:1], v[14:15], off offset:-1024
	v_cvt_pk_bf16_f32 v18, v18, v19
	v_cvt_pk_bf16_f32 v19, v20, v21
	global_store_dwordx2 v[0:1], v[18:19], off offset:-512
	v_cvt_pk_bf16_f32 v22, v22, v23
	v_cvt_pk_bf16_f32 v23, v24, v25
	global_store_dwordx2 v[0:1], v[22:23], off
	v_lshl_add_u64 v[0:1], v[0:1], 0, s[2:3]
	s_cmpk_gt_i32 s0, 0x3fff
	s_cbranch_scc0 .LBB0_569
